# att18 = att17 + next unit-map's Q fragments prefetched at the final step too; prefetched prologue issues only V0 and its step-0 waits skip vmcnt
# speedup vs baseline: 1.0053x; 1.0020x over previous
.Lkp_skip1:
	v_lshl_or_b32 v0, v252, 4, v0
	s_cmp_lg_u32 s100, 0
	s_cbranch_scc1 .Lqp_skipq
	global_load_dwordx4 v[188:191], v0, s[2:3]
	global_load_dwordx4 v[184:187], v0, s[2:3] offset:32
	global_load_dwordx4 v[176:179], v0, s[2:3] offset:64
	global_load_dwordx4 v[168:171], v0, s[2:3] offset:96
.Lqp_skipq:
	v_mov_b32_e32 v2, v1
	v_mov_b32_e32 v3, v1
	v_mov_b32_e32 v4, v1
	v_mov_b32_e32 v5, v1
	v_mov_b32_e32 v6, v1
	v_mov_b32_e32 v7, v1
	v_mov_b32_e32 v8, v1
	v_mov_b32_e32 v9, v1
	v_mov_b32_e32 v10, v1
	v_mov_b32_e32 v11, v1
	v_mov_b32_e32 v12, v1
	v_mov_b32_e32 v13, v1
	v_mov_b32_e32 v14, v1
	v_mov_b32_e32 v15, v1
	v_lshlrev_b32_e32 v0, 10, v252
	v_lshlrev_b32_e32 v16, 4, v236
	v_add3_u32 v247, 0, v0, v16
	v_mov_b32_e32 v0, v1
	v_mov_b64_e32 v[16:17], v[14:15]
	v_mov_b64_e32 v[14:15], v[12:13]
	v_mov_b64_e32 v[12:13], v[10:11]
	v_mov_b64_e32 v[10:11], v[8:9]
	v_mov_b64_e32 v[8:9], v[6:7]
	v_mov_b64_e32 v[6:7], v[4:5]
	v_mov_b64_e32 v[4:5], v[2:3]
	v_mov_b64_e32 v[2:3], v[0:1]
	v_lshl_add_u64 v[18:19], v[224:225], 0, s[10:11]
	s_add_i32 s1, s46, 0x4000
	s_cmp_lg_u32 s100, 0
	s_cbranch_scc1 .Lkp_skip2
	s_mov_b32 s2, m0
	s_mov_b32 m0, s1
	s_nop 0
	global_load_lds_dwordx4 v[18:19], off
	s_mov_b32 m0, s2
.Lkp_skip2:
	s_cmp_lg_u32 s100, 0
	s_cbranch_scc1 .Lqp_wb
	s_waitcnt vmcnt(3) lgkmcnt(0)
	s_branch .Lqp_wb2
.Lqp_wb:
	s_waitcnt vmcnt(2) lgkmcnt(0)
.Lqp_wb2:
	s_barrier
	s_cmp_lg_u32 s100, 0
	s_cbranch_scc0 .Lqp_nomov
	v_mov_b64_e32 v[184:185], v[192:193]
	v_mov_b64_e32 v[186:187], v[194:195]
	v_mov_b64_e32 v[176:177], v[196:197]
	v_mov_b64_e32 v[178:179], v[198:199]
	v_mov_b64_e32 v[168:169], v[200:201]
	v_mov_b64_e32 v[170:171], v[202:203]
.Lqp_nomov:
	ds_read_b128 v[36:39], v247
	v_or_b32_e32 v242, s38, v236
	s_andn2_b64 vcc, exec, s[54:55]
	v_lshlrev_b32_e32 v237, 2, v252
	s_waitcnt vmcnt(3) lgkmcnt(0)
	v_mfma_f32_32x32x16_bf16 v[18:33], v[36:39], v[188:191], v[2:17]
	ds_read_b128 v[36:39], v247 offset:512
	s_waitcnt lgkmcnt(0)
	v_mfma_f32_32x32x16_bf16 v[2:17], v[36:39], v[188:191], v[2:17]
	ds_read_b128 v[36:39], v247 offset:2048
	s_waitcnt vmcnt(2) lgkmcnt(0)
	v_mfma_f32_32x32x16_bf16 v[18:33], v[36:39], v[184:187], v[18:33]
	ds_read_b128 v[36:39], v247 offset:2560
	s_waitcnt lgkmcnt(0)
	v_mfma_f32_32x32x16_bf16 v[2:17], v[36:39], v[184:187], v[2:17]
	ds_read_b128 v[36:39], v247 offset:4096
	s_waitcnt lgkmcnt(0)
	s_cmp_lg_u32 s100, 0
	s_cbranch_scc1 .Lqp_w1
	s_waitcnt vmcnt(1)
.Lqp_w1:
	v_mfma_f32_32x32x16_bf16 v[18:33], v[36:39], v[176:179], v[18:33]
	ds_read_b128 v[36:39], v247 offset:4608
	s_waitcnt lgkmcnt(0)
	v_mfma_f32_32x32x16_bf16 v[2:17], v[36:39], v[176:179], v[2:17]
	ds_read_b128 v[36:39], v247 offset:6144
	s_waitcnt lgkmcnt(0)
	s_cmp_lg_u32 s100, 0
	s_cbranch_scc1 .Lqp_w0
	s_waitcnt vmcnt(0)
.Lqp_w0:
	v_mfma_f32_32x32x16_bf16 v[18:33], v[36:39], v[168:171], v[18:33]
	ds_read_b128 v[36:39], v247 offset:6656
	s_waitcnt lgkmcnt(0)
	v_mfma_f32_32x32x16_bf16 v[2:17], v[36:39], v[168:171], v[2:17]
	s_nop 15
	s_nop 7
	s_cbranch_vccnz .LBB0_298
	v_lshlrev_b32_e32 v0, 2, v252
	v_subrev_u32_e32 v0, s34, v0
	v_or_b32_e32 v36, 32, v0
	v_cmp_le_i32_e32 vcc, v36, v242
	v_or_b32_e32 v36, 33, v0
	s_nop 5
	v_cndmask_b32_e32 v2, v231, v2, vcc
	v_cmp_lt_i32_e32 vcc, v0, v242
	s_nop 1
	v_cndmask_b32_e32 v19, v231, v19, vcc
	v_cmp_le_i32_e32 vcc, v0, v242
	s_nop 1
	v_cndmask_b32_e32 v18, v231, v18, vcc
	v_cmp_le_i32_e32 vcc, v36, v242
	v_or_b32_e32 v36, 2, v0
	s_nop 0
	v_cndmask_b32_e32 v3, v231, v3, vcc
	v_cmp_le_i32_e32 vcc, v36, v242
	v_or_b32_e32 v36, 34, v0
	s_nop 0
	v_cndmask_b32_e32 v20, v231, v20, vcc
	v_cmp_le_i32_e32 vcc, v36, v242
	v_or_b32_e32 v36, 3, v0
	s_nop 0
	v_cndmask_b32_e32 v4, v231, v4, vcc
	v_cmp_le_i32_e32 vcc, v36, v242
	v_or_b32_e32 v36, 35, v0
	s_nop 0
	v_cndmask_b32_e32 v21, v231, v21, vcc
	v_cmp_le_i32_e32 vcc, v36, v242
	v_or_b32_e32 v36, 8, v0
	s_nop 0
	v_cndmask_b32_e32 v5, v231, v5, vcc
	v_cmp_le_i32_e32 vcc, v36, v242
	v_or_b32_e32 v36, 40, v0
	s_nop 0
	v_cndmask_b32_e32 v22, v231, v22, vcc
	v_cmp_le_i32_e32 vcc, v36, v242
	v_or_b32_e32 v36, 9, v0
	s_nop 0
	v_cndmask_b32_e32 v6, v231, v6, vcc
	v_cmp_le_i32_e32 vcc, v36, v242
	v_or_b32_e32 v36, 41, v0
	s_nop 0
	v_cndmask_b32_e32 v23, v231, v23, vcc
	v_cmp_le_i32_e32 vcc, v36, v242
	v_or_b32_e32 v36, 10, v0
	s_nop 0
	v_cndmask_b32_e32 v7, v231, v7, vcc
	v_cmp_le_i32_e32 vcc, v36, v242
	v_or_b32_e32 v36, 42, v0
	s_nop 0
	v_cndmask_b32_e32 v24, v231, v24, vcc
	v_cmp_le_i32_e32 vcc, v36, v242
	v_or_b32_e32 v36, 11, v0
	s_nop 0
	v_cndmask_b32_e32 v8, v231, v8, vcc
	v_cmp_le_i32_e32 vcc, v36, v242
	v_or_b32_e32 v36, 43, v0
	s_nop 0
	v_cndmask_b32_e32 v25, v231, v25, vcc
	v_cmp_le_i32_e32 vcc, v36, v242
	v_or_b32_e32 v36, 16, v0
	s_nop 0
	v_cndmask_b32_e32 v9, v231, v9, vcc
	v_cmp_le_i32_e32 vcc, v36, v242
	v_or_b32_e32 v36, 48, v0
	s_nop 0
	v_cndmask_b32_e32 v26, v231, v26, vcc
	v_cmp_le_i32_e32 vcc, v36, v242
	v_or_b32_e32 v36, 17, v0
	s_nop 0
	v_cndmask_b32_e32 v10, v231, v10, vcc
	v_cmp_le_i32_e32 vcc, v36, v242
	v_or_b32_e32 v36, 49, v0
	s_nop 0
	v_cndmask_b32_e32 v27, v231, v27, vcc
	v_cmp_le_i32_e32 vcc, v36, v242
	v_or_b32_e32 v36, 18, v0
	s_nop 0
	v_cndmask_b32_e32 v11, v231, v11, vcc
	v_cmp_le_i32_e32 vcc, v36, v242
	v_or_b32_e32 v36, 50, v0
	s_nop 0
	v_cndmask_b32_e32 v28, v231, v28, vcc
	v_cmp_le_i32_e32 vcc, v36, v242
	v_or_b32_e32 v36, 19, v0
	s_nop 0
	v_cndmask_b32_e32 v12, v231, v12, vcc
	v_cmp_le_i32_e32 vcc, v36, v242
	v_or_b32_e32 v36, 51, v0
	s_nop 0
	v_cndmask_b32_e32 v29, v231, v29, vcc
	v_cmp_le_i32_e32 vcc, v36, v242
	v_or_b32_e32 v36, 24, v0
	s_nop 0
	v_cndmask_b32_e32 v13, v231, v13, vcc
	v_cmp_le_i32_e32 vcc, v36, v242
	v_or_b32_e32 v36, 56, v0
	s_nop 0
	v_cndmask_b32_e32 v30, v231, v30, vcc
	v_cmp_le_i32_e32 vcc, v36, v242
	v_or_b32_e32 v36, 25, v0
	s_nop 0
	v_cndmask_b32_e32 v14, v231, v14, vcc
	v_cmp_le_i32_e32 vcc, v36, v242
	v_or_b32_e32 v36, 57, v0
	s_nop 0
	v_cndmask_b32_e32 v31, v231, v31, vcc
	v_cmp_le_i32_e32 vcc, v36, v242
	v_or_b32_e32 v36, 26, v0
	s_nop 0
	v_cndmask_b32_e32 v15, v231, v15, vcc
	v_cmp_le_i32_e32 vcc, v36, v242
	v_or_b32_e32 v36, 58, v0
	s_nop 0
	v_cndmask_b32_e32 v32, v231, v32, vcc
	v_cmp_le_i32_e32 vcc, v36, v242
	v_or_b32_e32 v36, 27, v0
	v_or_b32_e32 v0, 59, v0
	v_cndmask_b32_e32 v16, v231, v16, vcc
	v_cmp_le_i32_e32 vcc, v36, v242
	s_nop 1
	v_cndmask_b32_e32 v33, v231, v33, vcc
	v_cmp_le_i32_e32 vcc, v0, v242
	s_nop 1
	v_cndmask_b32_e32 v17, v231, v17, vcc

.Lkp_m1:
	v_and_b32_e32 v253, 63, v244
	v_lshlrev_b32_e32 v253, 11, v253
	v_lshrrev_b32_e32 v255, 6, v244
	v_lshl_add_u32 v253, v255, 4, v253
	s_mov_b32 s101, m0
	s_mov_b32 m0, s46
	s_nop 0
	global_load_lds_dwordx4 v253, s[98:99]
	s_add_u32 s98, s98, 0x20000
	s_addc_u32 s99, s99, 0
	s_add_i32 m0, s46, 0x2000
	s_nop 0
	global_load_lds_dwordx4 v253, s[98:99]
	s_add_u32 s98, s98, 0x20000
	s_addc_u32 s99, s99, 0
	s_add_i32 m0, s46, 0x4000
	s_nop 0
	global_load_lds_dwordx4 v253, s[98:99]
	s_mov_b32 m0, s101
	s_mov_b32 s98, s35
	s_mov_b32 s99, s84
	s_add_i32 s101, s31, 64
	s_cmp_lg_u64 s[72:73], 0
	s_cbranch_scc0 .Lqp_rows
	s_mov_b32 s101, s31
	v_readlane_b32 s98, v254, 41
	s_cmp_eq_u32 s27, 1
	s_cbranch_scc0 .Lqp_n2
	v_readlane_b32 s98, v254, 42
.Lqp_n2:
	s_cmp_eq_u32 s27, 2
	s_cbranch_scc0 .Lqp_n3
	v_readlane_b32 s98, v254, 44
.Lqp_n3:
	s_nop 3
	s_lshl_b32 s98, s98, 8
	s_sub_u32 s99, s35, s34
	s_add_u32 s98, s99, s98
	s_mov_b32 s99, s84
.Lqp_rows:
	v_readfirstlane_b32 s100, v244
	s_nop 3
	s_lshr_b32 s100, s100, 6
	s_lshl_b32 s100, s100, 5
	s_add_u32 s98, s98, s100
	s_addc_u32 s99, s99, 0
	s_lshl_b64 s[98:99], s[98:99], 11
	s_add_u32 s98, s98, s94
	s_addc_u32 s99, s99, s95
	s_lshl_b32 s101, s101, 1
	s_add_u32 s98, s98, s101
	s_addc_u32 s99, s99, 0
	v_and_b32_e32 v226, 31, v244
	v_lshlrev_b32_e32 v226, 11, v226
	v_bfe_u32 v227, v244, 5, 1
	v_lshl_or_b32 v226, v227, 4, v226
	global_load_dwordx4 v[188:191], v226, s[98:99]
	global_load_dwordx4 v[192:195], v226, s[98:99] offset:32
	global_load_dwordx4 v[196:199], v226, s[98:99] offset:64
	global_load_dwordx4 v[200:203], v226, s[98:99] offset:96
	s_mov_b32 s100, 1
